# v16_fold
# baseline (speedup 1.0000x reference)
; __device__ __forceinline__ float bf2f(u16 b) { return __uint_as_float(((unsigned)b) << 16); }
; __device__ __forceinline__ float bflo(unsigned w) { return __uint_as_float(w << 16); }
; __device__ __forceinline__ float bfhi(unsigned w) { return __uint_as_float(w & 0xffff0000u); }
; __device__ __forceinline__ void phase_fold(const Params& p, int bid, int G, int tid) {
;     ...
;         if (x0 <= L / 2) {
;             const u32x4 a0 = *(const u32x4*)(src + x0);
;             if (x0 == L / 2) ov[0] = pq ? 0.f : bflo(a0.x);
;             else {
;                 const u32x4 a1 = *(const u32x4*)(src + x0 + 8), r0 = *(const u32x4*)(src + L - x0 - 16), r1 = *(const u32x4*)(src + L - x0 - 8);
;                 const float av[16] = {bflo(a0.x), bfhi(a0.x), bflo(a0.y), bfhi(a0.y), bflo(a0.z), bfhi(a0.z), bflo(a0.w), bfhi(a0.w), bflo(a1.x), bfhi(a1.x), bflo(a1.y), bfhi(a1.y), bflo(a1.z), bfhi(a1.z), bflo(a1.w), bfhi(a1.w)};
;                 const float rv[16] = {bflo(r0.x), bfhi(r0.x), bflo(r0.y), bfhi(r0.y), bflo(r0.z), bfhi(r0.z), bflo(r0.w), bfhi(r0.w), bflo(r1.x), bfhi(r1.x), bflo(r1.y), bfhi(r1.y), bflo(r1.z), bfhi(r1.z), bflo(r1.w), bfhi(r1.w)};
;                 const float e0 = x0 ? bf2f(src[L - x0]) : 0.f;
;                 if (x0 == 0) ov[0] = pq ? 0.f : av[0]; else ov[0] = pq ? av[0] - e0 : av[0] + e0;
.LBB0_289:
	s_or_b64 exec, exec, s[6:7]
	v_lshlrev_b32_e32 v22, 4, v26
	v_lshrrev_b32_e32 v35, 1, v34
	v_cmp_le_i32_e32 vcc, v22, v35
	v_mov_b32_e32 v21, 0
	v_mov_b32_e32 v6, 0
	v_mov_b32_e32 v16, 0
	v_mov_b32_e32 v7, 0
	v_mov_b32_e32 v17, 0
	v_mov_b32_e32 v8, 0
	v_mov_b32_e32 v28, 0
	v_mov_b32_e32 v9, 0
	v_mov_b32_e32 v29, 0
	v_mov_b32_e32 v12, 0
	v_mov_b32_e32 v30, 0
	v_mov_b32_e32 v14, 0
	v_mov_b32_e32 v31, 0
	v_mov_b32_e32 v15, 0
	v_mov_b32_e32 v32, 0
	v_mov_b32_e32 v13, 0
	s_and_saveexec_b64 s[6:7], vcc
	s_cbranch_execz .LBB0_284
	v_and_b32_e32 v33, 0x3ff, v27
	v_lshlrev_b32_e32 v4, 16, v33
	v_mov_b32_e32 v5, v0
	v_lshl_add_u64 v[4:5], s[88:89], 0, v[4:5]
	v_ashrrev_i32_e32 v3, 31, v2
	v_lshl_add_u64 v[2:3], v[2:3], 1, v[4:5]
	s_mov_b64 s[8:9], 0x1c000000
	v_lshl_add_u64 v[24:25], v[2:3], 0, s[8:9]
	v_ashrrev_i32_e32 v23, 31, v22
	v_lshl_add_u64 v[10:11], v[22:23], 1, v[24:25]
	global_load_dwordx4 v[2:5], v[10:11], off
	v_cmp_ne_u32_e32 vcc, v22, v35
	s_and_saveexec_b64 s[8:9], vcc
	s_xor_b64 s[8:9], exec, s[8:9]
	s_cbranch_execz .LBB0_296
	v_lshlrev_b32_e32 v6, 1, v34
	v_mov_b32_e32 v7, v0
	v_lshl_add_u64 v[6:7], v[24:25], 0, v[6:7]
	v_lshlrev_b64 v[8:9], 1, v[22:23]
	v_sub_co_u32_e32 v12, vcc, v6, v8
	s_nop 1
	v_subb_co_u32_e32 v13, vcc, v7, v9, vcc
	global_load_dwordx4 v[6:9], v[12:13], off offset:-16
	global_load_dwordx4 v[14:17], v[10:11], off offset:16
	s_nop 0
	global_load_dwordx4 v[10:13], v[12:13], off offset:-32
	s_waitcnt vmcnt(3)
	v_lshlrev_b32_e32 v35, 16, v2
	v_cmp_ne_u32_e32 vcc, 0, v26
	s_and_saveexec_b64 s[10:11], vcc
	s_xor_b64 s[10:11], exec, s[10:11]
	s_cbranch_execz .LBB0_293
	v_sub_u32_e32 v22, v34, v22
	v_mov_b32_e32 v23, v0
	v_lshl_add_u64 v[22:23], v[22:23], 1, v[24:25]
	global_load_ushort v21, v[22:23], off
	s_movk_i32 s12, 0x200
	v_cmp_gt_u32_e32 vcc, s12, v33
	s_waitcnt vmcnt(0)
	v_lshlrev_b32_e32 v21, 16, v21
	v_cndmask_b32_e64 v21, -v21, v21, vcc
	v_add_f32_e32 v21, v21, v35

; __device__ __forceinline__ float bflo(unsigned w) { return __uint_as_float(w << 16); }
; __device__ __forceinline__ void phase_fold(const Params& p, int bid, int G, int tid) {
;     ...
;         float ov[16];
; #pragma unroll
;         for (int m = 0; m < 16; ++m) ov[m] = 0.f;
;         if (x0 <= L / 2) {
;             const u32x4 a0 = *(const u32x4*)(src + x0);
;             if (x0 == L / 2) ov[0] = pq ? 0.f : bflo(a0.x);
.LBB0_296:
	s_andn2_saveexec_b64 s[8:9], s[8:9]
	s_cbranch_execz .LBB0_283
	s_waitcnt vmcnt(0)
	v_lshlrev_b32_e32 v35, 16, v2
	s_movk_i32 s10, 0x200
	v_cmp_gt_u32_e32 vcc, s10, v33
	v_mov_b32_e32 v13, 0
	v_mov_b32_e32 v32, 0
	v_cndmask_b32_e32 v21, 0, v35, vcc
	v_mov_b32_e32 v15, 0
	v_mov_b32_e32 v31, 0
	v_mov_b32_e32 v14, 0
	v_mov_b32_e32 v30, 0
	v_mov_b32_e32 v12, 0
	v_mov_b32_e32 v29, 0
	v_mov_b32_e32 v9, 0
	v_mov_b32_e32 v28, 0
	v_mov_b32_e32 v8, 0
	v_mov_b32_e32 v17, 0
	v_mov_b32_e32 v7, 0
	v_mov_b32_e32 v16, 0
	v_mov_b32_e32 v6, 0
	s_branch .LBB0_283
